# block-id permutation so neighbouring workgroups share the weight tile (k -> ((k&31)<<1)|(k>>5)) on top of producer/consumer GEMMs + hand-written merge
# speedup vs baseline: 1.0654x; 1.0148x over previous
.Lab_skip:
	s_or_b64 exec, exec, s[2:3]
	s_waitcnt lgkmcnt(0)
	s_barrier
	v_mov_b32_e32 v1, 0x10018
	ds_read_b32 v1, v1
	v_lshrrev_b32_e32 v2, 6, v194
	s_waitcnt lgkmcnt(0)
	s_nop 0
	v_readfirstlane_b32 s101, v1
	v_readfirstlane_b32 s100, v2
	s_getreg_b32 s98, hwreg(HW_REG_HW_ID, 4, 2)
	s_getreg_b32 s99, hwreg(HW_REG_HW_ID, 0, 1)
	s_lshl_b32 s99, s99, 4
	s_or_b32 s99, s99, s98
	v_mov_b32_e32 v1, s99
	v_lshlrev_b32_e32 v2, 2, v2
	v_add_u32_e32 v2, 0x10000, v2
	ds_write_b32 v2, v1
	s_waitcnt lgkmcnt(0)
	s_barrier
	v_mov_b32_e32 v2, 0x10000
	ds_read_b32 v1, v2
	ds_read_b32 v3, v2 offset:4
	ds_read_b32 v4, v2 offset:8
	ds_read_b32 v5, v2 offset:12
	s_waitcnt lgkmcnt(0)
	v_and_b32_e32 v6, v1, v3
	v_and_b32_e32 v7, v4, v5
	v_and_b32_e32 v6, v6, v7
	v_or3_b32 v7, v1, v3, v4
	v_or_b32_e32 v7, v7, v5
	v_xor_b32_e32 v6, v6, v7
	v_and_b32_e32 v1, 3, v1
	v_and_b32_e32 v3, 3, v3
	v_and_b32_e32 v4, 3, v4
	v_and_b32_e32 v5, 3, v5
	v_lshlrev_b32_e64 v1, v1, 1
	v_lshlrev_b32_e64 v3, v3, 1
	v_lshlrev_b32_e64 v4, v4, 1
	v_lshlrev_b32_e64 v5, v5, 1
	v_or3_b32 v1, v1, v3, v4
	v_or_b32_e32 v1, v1, v5
	s_nop 0
	v_readfirstlane_b32 s99, v1
	v_readfirstlane_b32 vcc_lo, v6
	s_bitcmp1_b32 vcc_lo, 4
	s_cbranch_scc1 .Lab_keep
	s_getreg_b32 s101, hwreg(HW_REG_HW_ID, 0, 1)
.Lab_keep:
	s_cmp_eq_u32 s99, 15
	s_cbranch_scc1 .Lrole_simd
	s_cmp_lt_u32 s100, 2
	s_cselect_b32 s99, 1, 0
	s_and_b32 s98, s100, 1
	s_branch .Lrole_done

.Lrole_done:
	s_lshl_b32 s98, s98, 1
	s_or_b32 s99, s99, s98
	s_lshl_b32 s100, s100, 2
	s_or_b32 s101, s99, s100
	v_readlane_b32 s98, v252, 0
	s_lshr_b32 s98, s98, 3
	s_and_b32 s98, s98, 0xff
	s_lshl_b32 s98, s98, 8
	s_or_b32 s101, s101, s98
	v_readlane_b32 s98, v252, 0
	s_lshr_b32 s99, s98, 3
	s_and_b32 s98, s98, 7
	s_and_b32 s100, s99, 31
	s_lshl_b32 s100, s100, 1
	s_lshr_b32 s99, s99, 5
	s_or_b32 s99, s99, s100
	s_lshl_b32 s99, s99, 3
	s_or_b32 s98, s98, s99
	s_nop 0
	v_writelane_b32 v252, s98, 0
	s_load_dwordx2 s[52:53], s[0:1], 0x210
	s_waitcnt lgkmcnt(0)
	s_cmp_ge_i32 s52, s53
	s_cbranch_scc1 .Lend_near
	s_load_dwordx2 s[22:23], s[0:1], 0x1a8
	s_load_dwordx16 s[56:71], s[0:1], 0x0
	s_load_dwordx16 s[36:51], s[0:1], 0x40
	s_load_dwordx16 s[4:19], s[0:1], 0x80
	v_lshrrev_b32_e32 v1, 20, v0
	v_lshrrev_b32_e32 v0, 10, v0
	v_or_b32_e32 v0, v0, v1
	s_mov_b32 s97, 0
	s_waitcnt lgkmcnt(0)
	v_writelane_b32 v252, s4, 5
	s_movk_i32 s55, 0x4000
	v_mov_b32_e32 v2, 0
	v_writelane_b32 v252, s5, 6
	v_writelane_b32 v252, s6, 7
	v_writelane_b32 v252, s7, 8
	v_writelane_b32 v252, s8, 9
	v_writelane_b32 v252, s9, 10
	v_writelane_b32 v252, s10, 11
	v_writelane_b32 v252, s11, 12
	v_writelane_b32 v252, s12, 13
	v_writelane_b32 v252, s13, 14
	v_writelane_b32 v252, s14, 15
	v_writelane_b32 v252, s15, 16
	v_writelane_b32 v252, s16, 17
	v_writelane_b32 v252, s17, 18
	v_writelane_b32 v252, s18, 19
	v_writelane_b32 v252, s19, 20
	s_load_dwordx16 s[4:19], s[0:1], 0xc0
	s_mov_b32 s28, 0x10000
	v_mov_b32_e32 v198, 0x358637bd
	s_movk_i32 s96, 0x43ff
	s_mov_b32 s29, 0x20000
	s_waitcnt lgkmcnt(0)
	v_writelane_b32 v252, s4, 21
	v_mov_b32_e32 v199, 0x10000
	s_movk_i32 s33, 0x110
	v_writelane_b32 v252, s5, 22
	v_writelane_b32 v252, s6, 23
	v_writelane_b32 v252, s7, 24
	v_writelane_b32 v252, s8, 25
	v_writelane_b32 v252, s9, 26
	v_writelane_b32 v252, s10, 27
	v_writelane_b32 v252, s11, 28
	v_writelane_b32 v252, s12, 29
	v_writelane_b32 v252, s13, 30
	v_writelane_b32 v252, s14, 31
	v_writelane_b32 v252, s15, 32
	v_writelane_b32 v252, s16, 33
	v_writelane_b32 v252, s17, 34
	v_writelane_b32 v252, s18, 35
	v_writelane_b32 v252, s19, 36
	s_load_dwordx16 s[4:19], s[0:1], 0x100
	v_mov_b32_e32 v201, 0x3ecc95a3
	v_mov_b64_e32 v[212:213], 0xe00
	v_mov_b64_e32 v[196:197], 0x3600
	v_mov_b32_e32 v204, 0x7f800000
	s_waitcnt lgkmcnt(0)
	v_writelane_b32 v252, s4, 37
	v_mov_b32_e32 v206, 0x41b17218
	v_mov_b32_e32 v136, 0x3f317218
	v_writelane_b32 v252, s5, 38
	v_writelane_b32 v252, s6, 39
	v_writelane_b32 v252, s7, 40
	v_writelane_b32 v252, s8, 41
	v_writelane_b32 v252, s9, 42
	v_writelane_b32 v252, s10, 43
	v_writelane_b32 v252, s11, 44
	v_writelane_b32 v252, s12, 45
	v_writelane_b32 v252, s13, 46
	v_writelane_b32 v252, s14, 47
	v_writelane_b32 v252, s15, 48
	v_writelane_b32 v252, s16, 49
	v_writelane_b32 v252, s17, 50
	v_writelane_b32 v252, s18, 51
	v_writelane_b32 v252, s19, 52
	s_load_dwordx16 s[72:87], s[0:1], 0x140
	s_load_dwordx16 s[4:19], s[0:1], 0x1b0
	v_mov_b32_e32 v203, 0x7fc00000
	v_mov_b32_e32 v195, 0xff800000
	v_mov_b32_e32 v205, 0xe400
	v_mov_b32_e32 v200, 0x9f00
	s_waitcnt lgkmcnt(0)
	v_writelane_b32 v252, s4, 53
	v_mov_b32_e32 v207, 0x42800000
	s_nop 0
	v_writelane_b32 v252, s5, 54
	v_writelane_b32 v252, s6, 55
	v_writelane_b32 v252, s7, 56
	v_writelane_b32 v253, s15, 0
	v_writelane_b32 v252, s8, 57
	v_writelane_b32 v253, s16, 1
	v_writelane_b32 v252, s9, 58
	v_writelane_b32 v253, s17, 2
	v_writelane_b32 v252, s10, 59
	v_writelane_b32 v253, s18, 3
	v_writelane_b32 v252, s11, 60
	v_writelane_b32 v253, s19, 4
	s_load_dwordx8 s[4:11], s[0:1], 0x1f0
	s_add_u32 s0, s0, 0x218
	s_addc_u32 s1, s1, 0
	v_writelane_b32 v252, s12, 61
	v_writelane_b32 v252, s13, 62
	s_waitcnt lgkmcnt(0)
	v_writelane_b32 v253, s4, 5
	v_writelane_b32 v252, s14, 63
	s_nop 0
	v_writelane_b32 v253, s5, 6
	v_writelane_b32 v253, s6, 7
	v_writelane_b32 v253, s7, 8
	v_writelane_b32 v253, s8, 9
	v_writelane_b32 v253, s9, 10
	v_writelane_b32 v253, s10, 11
	v_writelane_b32 v253, s11, 12
	v_writelane_b32 v253, s0, 13
	s_nop 1
	v_writelane_b32 v253, s1, 14
	s_add_u32 s0, s88, 0x200
	s_addc_u32 s1, s89, 0
	v_writelane_b32 v253, s0, 15
	s_nop 1
	v_writelane_b32 v253, s1, 16
	s_add_u32 s0, s88, 0x1000
	s_addc_u32 s1, s89, 0
	v_writelane_b32 v253, s0, 17
	s_nop 1
	v_writelane_b32 v253, s1, 18
	s_add_u32 s0, s88, 0x1100
	s_addc_u32 s1, s89, 0
	v_writelane_b32 v253, s0, 19
	s_nop 1
	v_writelane_b32 v253, s1, 20
	s_add_u32 s0, s88, 0x1200
	s_addc_u32 s1, s89, 0
	v_writelane_b32 v253, s0, 21
	s_nop 1
	v_writelane_b32 v253, s1, 22
	s_add_u32 s0, s88, 0x1300
	s_addc_u32 s1, s89, 0
	v_writelane_b32 v253, s0, 23
	s_cmp_eq_u32 s20, 15
	s_nop 0
	v_writelane_b32 v253, s1, 24
	s_cselect_b64 s[0:1], -1, 0
	v_writelane_b32 v253, s0, 25
	s_cmp_eq_u32 s20, 14
	s_nop 0
	v_writelane_b32 v253, s1, 26
	s_cselect_b64 s[0:1], -1, 0
	v_writelane_b32 v253, s0, 27
	s_cmp_eq_u32 s20, 13
	s_nop 0
	v_writelane_b32 v253, s1, 28
	s_cselect_b64 s[0:1], -1, 0
	v_writelane_b32 v253, s0, 29
	s_cmp_eq_u32 s20, 12
	s_nop 0
	v_writelane_b32 v253, s1, 30
	s_cselect_b64 s[0:1], -1, 0
	v_writelane_b32 v253, s0, 31
	s_cmp_eq_u32 s20, 11
	s_nop 0
	v_writelane_b32 v253, s1, 32
	s_cselect_b64 s[0:1], -1, 0
	v_writelane_b32 v253, s0, 33
	s_cmp_eq_u32 s20, 10
	s_nop 0
	v_writelane_b32 v253, s1, 34
	s_cselect_b64 s[0:1], -1, 0
	v_writelane_b32 v253, s0, 35
	s_cmp_eq_u32 s20, 9
	s_nop 0
	v_writelane_b32 v253, s1, 36
	s_cselect_b64 s[0:1], -1, 0
	v_writelane_b32 v253, s0, 37
	s_cmp_eq_u32 s20, 8
	s_nop 0
	v_writelane_b32 v253, s1, 38
	s_cselect_b64 s[0:1], -1, 0
	v_writelane_b32 v253, s0, 39
	s_cmp_eq_u32 s20, 7
	s_nop 0
	v_writelane_b32 v253, s1, 40
	s_cselect_b64 s[0:1], -1, 0
	v_writelane_b32 v253, s0, 41
	s_cmp_eq_u32 s20, 6
	s_nop 0
	v_writelane_b32 v253, s1, 42
	s_cselect_b64 s[0:1], -1, 0
	v_writelane_b32 v253, s0, 43
	s_cmp_eq_u32 s20, 5
	s_nop 0
	v_writelane_b32 v253, s1, 44
	s_cselect_b64 s[0:1], -1, 0
	v_writelane_b32 v253, s0, 45
	s_cmp_eq_u32 s20, 4
	s_nop 0
	v_writelane_b32 v253, s1, 46
	s_cselect_b64 s[0:1], -1, 0
	v_writelane_b32 v253, s0, 47
	s_cmp_eq_u32 s20, 3
	s_nop 0
	v_writelane_b32 v253, s1, 48
	s_cselect_b64 s[0:1], -1, 0
	v_writelane_b32 v253, s0, 49
	s_cmp_eq_u32 s20, 2
	s_nop 0
	v_writelane_b32 v253, s1, 50
	s_cselect_b64 s[0:1], -1, 0
	v_writelane_b32 v253, s0, 51
	s_cmp_eq_u32 s20, 1
	s_nop 0
	v_writelane_b32 v253, s1, 52
	s_cselect_b64 s[0:1], -1, 0
	v_writelane_b32 v253, s0, 53
	s_cmp_eq_u32 s20, 0
	s_nop 0
	v_writelane_b32 v253, s1, 54
	s_cselect_b64 s[0:1], -1, 0
	v_writelane_b32 v253, s0, 55
	s_nop 1
	v_writelane_b32 v253, s1, 56
	s_lshl_b32 s0, s20, 8
	s_add_u32 s0, s88, s0
	s_addc_u32 s1, s89, 0
	s_add_u32 s2, s0, 0x1400
	s_addc_u32 s3, s1, 0
	v_writelane_b32 v253, s2, 57
	s_add_u32 s0, s0, 0x2400
	s_addc_u32 s1, s1, 0
	v_writelane_b32 v253, s3, 58
	v_writelane_b32 v253, s0, 59
	v_readlane_b32 s3, v252, 0
	s_nop 0
	v_writelane_b32 v253, s1, 60
	s_add_u32 s0, s88, 0x3400
	s_addc_u32 s1, s89, 0
	v_writelane_b32 v253, s0, 61
	s_nop 1
	v_writelane_b32 v253, s1, 62
	s_add_u32 s0, s88, 0x3500
	s_addc_u32 s1, s89, 0
	v_writelane_b32 v253, s0, 63
	s_cmp_lt_i32 s53, 0
	s_nop 0
	v_writelane_b32 v254, s1, 0
	s_cselect_b64 s[0:1], -1, 0
	v_writelane_b32 v254, s0, 1
	s_nop 1
	v_writelane_b32 v254, s1, 2
	s_movk_i32 s0, 0x3ff
	v_and_or_b32 v0, v0, s0, v194
	v_cmp_eq_u32_e64 s[0:1], 0, v0
	s_nop 1
	v_writelane_b32 v254, s0, 3
	s_nop 1
	v_writelane_b32 v254, s1, 4
	s_lshl_b32 s0, s3, 2
	v_writelane_b32 v254, s0, 5
	s_add_u32 s0, s42, 0x1000
	v_writelane_b32 v254, s36, 6
	s_addc_u32 s1, s43, 0
	s_cmp_lg_u64 s[84:85], 0
	v_writelane_b32 v254, s37, 7
	v_writelane_b32 v254, s38, 8
	v_writelane_b32 v254, s39, 9
	v_writelane_b32 v254, s40, 10
	v_writelane_b32 v254, s41, 11
	v_writelane_b32 v254, s42, 12
	v_writelane_b32 v254, s43, 13
	v_writelane_b32 v254, s44, 14
	v_writelane_b32 v254, s45, 15
	v_writelane_b32 v254, s46, 16
	v_writelane_b32 v254, s47, 17
	v_writelane_b32 v254, s48, 18
	v_writelane_b32 v254, s49, 19
	v_writelane_b32 v254, s50, 20
	v_writelane_b32 v254, s51, 21
	v_writelane_b32 v254, s0, 22
	s_mov_b64 s[36:37], 0x800
	s_nop 0
	v_writelane_b32 v254, s1, 23
	s_cselect_b64 s[0:1], -1, 0
	v_writelane_b32 v254, s0, 24
	s_cmpk_lt_i32 s3, 0x1560
	s_nop 0
	v_writelane_b32 v254, s1, 25
	s_cselect_b64 s[0:1], -1, 0
	v_writelane_b32 v254, s0, 26
	s_cmp_lg_u64 s[76:77], 0
	s_nop 0
	v_writelane_b32 v254, s1, 27
	s_cselect_b64 s[0:1], -1, 0
	v_writelane_b32 v254, s0, 28
	s_and_b32 s4, s3, 7
	s_lshl_b32 s2, s3, 4
	v_writelane_b32 v254, s1, 29
	s_lshr_b32 s0, s3, 3
	s_lshl_b32 s1, s4, 6
	v_writelane_b32 v254, s0, 30
	s_add_i32 s0, s1, s0
	v_writelane_b32 v254, s1, 31
	s_lshl_b32 s0, s0, 4
	s_and_b32 s2, s2, 0x380
	s_and_b32 s1, s0, 0xfffffc00
	v_writelane_b32 v254, s2, 32
	s_and_b32 s0, s0, 0x380
	v_writelane_b32 v254, s0, 33
	s_lshl_b32 s0, s3, 1
	s_and_b32 s0, s0, 0x7fffff80
	s_or_b32 s1, s1, s2
	s_addk_i32 s0, 0x4000
	v_writelane_b32 v254, s0, 34
	s_add_i32 s54, s1, 0x2000
	s_lshl_b32 s0, s4, 22
	v_writelane_b32 v254, s1, 35
	s_add_u32 s0, s80, s0
	v_writelane_b32 v254, s4, 36
	s_addc_u32 s1, s81, 0
	v_writelane_b32 v254, s0, 37
	s_nop 1
	v_writelane_b32 v254, s1, 38
	s_add_i32 s1, s22, -1
	s_mul_i32 s0, s1, 0x60
	v_writelane_b32 v254, s0, 39
	s_mul_i32 s0, s1, 0xa0
	v_writelane_b32 v254, s0, 40
	s_ashr_i32 s0, s1, 31
	v_writelane_b32 v254, s0, 41
	v_writelane_b32 v254, s22, 42
	s_sub_i32 s0, 1, s22
	s_max_i32 s0, s1, s0
	v_cvt_f32_u32_e32 v0, s0
	v_writelane_b32 v254, s23, 43
	v_writelane_b32 v254, s1, 44
	v_writelane_b32 v254, s0, 45
	v_rcp_iflag_f32_e32 v0, v0
	s_sub_i32 s0, 0, s0
	v_mul_f32_e32 v0, 0x4f7ffffe, v0
	v_cvt_u32_f32_e32 v0, v0
	s_nop 0
	v_readfirstlane_b32 s1, v0
	s_mul_i32 s0, s0, s1
	s_mul_hi_u32 s0, s1, s0
	s_add_i32 s0, s1, s0
	v_writelane_b32 v254, s0, 46
	s_add_u32 s0, s78, 64
	s_addc_u32 s1, s79, 0
	v_writelane_b32 v254, s0, 47
	v_mbcnt_lo_u32_b32 v0, -1, 0
	s_nop 0
	v_writelane_b32 v254, s1, 48
	v_readlane_b32 s0, v252, 1
	v_readlane_b32 s1, v252, 2
	s_add_u32 s2, s0, 0x100
	s_addc_u32 s3, s1, 0
	v_writelane_b32 v254, s2, 49
	v_mbcnt_hi_u32_b32 v202, -1, v0
	s_nop 0
	v_writelane_b32 v254, s3, 50
	s_add_u32 s2, s0, 0x140
	s_addc_u32 s3, s1, 0
	v_writelane_b32 v254, s2, 51
	s_nop 1
	v_writelane_b32 v254, s3, 52
	s_add_u32 s2, s0, 0x180
	s_addc_u32 s3, s1, 0
	v_writelane_b32 v254, s2, 53
	s_add_u32 s0, s0, 0x1c0
	s_addc_u32 s1, s1, 0
	v_writelane_b32 v254, s3, 54
	v_writelane_b32 v254, s0, 55
	s_mov_b32 s2, s52
	s_nop 0
	v_writelane_b32 v254, s1, 56
	s_add_u32 s0, s78, 0x2c00
	s_addc_u32 s1, s79, 0
	v_writelane_b32 v254, s0, 57
	s_nop 1
	v_writelane_b32 v254, s1, 58
	v_writelane_b32 v254, s54, 59
	v_writelane_b32 v254, s52, 60
	s_nop 1
	v_writelane_b32 v254, s53, 61
	s_branch .LBB0_9
